# v22: + EpiVT duplicate bias reloads replaced by register copies
# baseline (speedup 1.0000x reference)
;     __device__ __forceinline__ void operator()(const f32x4 (&acc)[2][2][4][2], const Unit& u, int wr, int wc, int fr, int fq) const {
;         const int row0 = u.pm * BM + wr * 64 + fr - row_off; const int col0 = u.pn * BM + wc * 32 + 8 * fq;
;         f32x4 r0[2], r1[2];
; #pragma unroll
;         for (int bj = 0; bj < 2; ++bj) { const unsigned long long* rp = rowsq + col0 + bj * HALF;
; #pragma unroll
;             for (int e = 0; e < 4; ++e) { r0[bj][e] = __builtin_amdgcn_rsqf((float)rp[e] * (1.f / 1024.f / 4294967296.f) + 1e-6f); r1[bj][e] = __builtin_amdgcn_rsqf((float)rp[4 + e] * (1.f / 1024.f / 4294967296.f) + 1e-6f); } }
; #pragma unroll
;         for (int ai = 0; ai < 2; ++ai)
; #pragma unroll
;             for (int m = 0; m < 4; ++m) { const int f = row0 + ai * HALF + m * 16; if (f < 0) continue; const int kvh = f >> 6, d = f & 63;
.LBB0_328:
	s_lshl_b32 s17, s24, 8
	s_or_b32 s17, s17, s59
	v_or_b32_e32 v130, s17, v180
	v_ashrrev_i32_e32 v131, 31, v130
	v_lshl_add_u64 v[142:143], v[130:131], 3, s[8:9]
	global_load_dwordx4 v[130:133], v[142:143], off offset:48
	global_load_dwordx4 v[134:137], v[142:143], off offset:32
	global_load_dwordx4 v[138:141], v[142:143], off offset:16
	global_load_dwordx4 v[174:177], v[142:143], off
	s_ashr_i32 s19, s24, 4
	s_and_b32 s17, s17, 0xf60
	s_waitcnt vmcnt(0)
	v_ffbh_u32_e32 v0, v175
	v_min_u32_e32 v0, 32, v0
	v_lshlrev_b64 v[144:145], v0, v[174:175]
	v_min_u32_e32 v144, 1, v144
	v_or_b32_e32 v144, v145, v144
	v_cvt_f32_u32_e32 v144, v144
	v_sub_u32_e32 v0, 32, v0
	v_ldexp_f32 v0, v144, v0
	v_fmamk_f32 v0, v0, 0x2a800000, v204
	v_rsq_f32_e32 v172, v0
	v_ffbh_u32_e32 v0, v135
	v_min_u32_e32 v0, 32, v0
	v_lshlrev_b64 v[134:135], v0, v[134:135]
	v_min_u32_e32 v134, 1, v134
	v_or_b32_e32 v134, v135, v134
	v_cvt_f32_u32_e32 v134, v134
	v_sub_u32_e32 v0, 32, v0
	v_ldexp_f32 v0, v134, v0
	v_fmamk_f32 v0, v0, 0x2a800000, v204
	v_rsq_f32_e32 v174, v0
	v_ffbh_u32_e32 v0, v177
	v_min_u32_e32 v0, 32, v0
	v_lshlrev_b64 v[134:135], v0, v[176:177]
	v_min_u32_e32 v134, 1, v134
	v_or_b32_e32 v134, v135, v134
	v_cvt_f32_u32_e32 v134, v134
	v_sub_u32_e32 v0, 32, v0
	v_ldexp_f32 v0, v134, v0
	v_fmamk_f32 v0, v0, 0x2a800000, v204
	v_rsq_f32_e32 v173, v0
	v_ffbh_u32_e32 v0, v137
	v_min_u32_e32 v0, 32, v0
	v_lshlrev_b64 v[134:135], v0, v[136:137]
	v_min_u32_e32 v134, 1, v134
	v_or_b32_e32 v134, v135, v134
	v_cvt_f32_u32_e32 v134, v134
	v_sub_u32_e32 v0, 32, v0
	v_ldexp_f32 v0, v134, v0
	v_fmamk_f32 v0, v0, 0x2a800000, v204
	v_rsq_f32_e32 v175, v0
	v_ffbh_u32_e32 v0, v139
	v_min_u32_e32 v0, 32, v0
	v_lshlrev_b64 v[134:135], v0, v[138:139]
	v_min_u32_e32 v134, 1, v134
	v_or_b32_e32 v134, v135, v134
	v_cvt_f32_u32_e32 v134, v134
	v_sub_u32_e32 v0, 32, v0
	v_ldexp_f32 v0, v134, v0
	v_fmamk_f32 v0, v0, 0x2a800000, v204
	v_rsq_f32_e32 v176, v0
	v_ffbh_u32_e32 v0, v131
	v_min_u32_e32 v0, 32, v0
	v_lshlrev_b64 v[130:131], v0, v[130:131]
	v_min_u32_e32 v130, 1, v130
	v_or_b32_e32 v130, v131, v130
	v_cvt_f32_u32_e32 v130, v130
	v_sub_u32_e32 v0, 32, v0
	v_ldexp_f32 v0, v130, v0
	v_fmamk_f32 v0, v0, 0x2a800000, v204
	v_rsq_f32_e32 v178, v0
	v_ffbh_u32_e32 v0, v141
	v_min_u32_e32 v0, 32, v0
	v_lshlrev_b64 v[130:131], v0, v[140:141]
	v_min_u32_e32 v130, 1, v130
	v_or_b32_e32 v130, v131, v130
	v_cvt_f32_u32_e32 v130, v130
	v_sub_u32_e32 v0, 32, v0
	v_ldexp_f32 v0, v130, v0
	v_fmamk_f32 v0, v0, 0x2a800000, v204
	v_rsq_f32_e32 v177, v0
	v_ffbh_u32_e32 v0, v133
	v_min_u32_e32 v0, 32, v0
	v_lshlrev_b64 v[130:131], v0, v[132:133]
	v_min_u32_e32 v130, 1, v130
	v_or_b32_e32 v130, v131, v130
	v_cvt_f32_u32_e32 v130, v130
	v_sub_u32_e32 v0, 32, v0
	v_ldexp_f32 v0, v130, v0
	global_load_dwordx4 v[130:133], v[142:143], off offset:1072
	global_load_dwordx4 v[138:141], v[142:143], off offset:1056
	global_load_dwordx4 v[134:137], v[142:143], off offset:1040
	s_nop 0
	global_load_dwordx4 v[142:145], v[142:143], off offset:1024
	v_fmamk_f32 v0, v0, 0x2a800000, v204
	v_rsq_f32_e32 v179, v0
	s_waitcnt vmcnt(0)
	v_ffbh_u32_e32 v0, v143
	v_min_u32_e32 v0, 32, v0
	v_lshlrev_b64 v[142:143], v0, v[142:143]
	v_min_u32_e32 v142, 1, v142
	v_or_b32_e32 v142, v143, v142
	v_cvt_f32_u32_e32 v142, v142
	v_sub_u32_e32 v0, 32, v0
	v_ldexp_f32 v0, v142, v0
	v_fmamk_f32 v0, v0, 0x2a800000, v204
	v_rsq_f32_e32 v142, v0
	v_ffbh_u32_e32 v0, v139
	v_min_u32_e32 v0, 32, v0
	v_lshlrev_b64 v[138:139], v0, v[138:139]
	v_min_u32_e32 v138, 1, v138
	v_or_b32_e32 v138, v139, v138
	v_cvt_f32_u32_e32 v138, v138
	v_sub_u32_e32 v0, 32, v0
	v_ldexp_f32 v0, v138, v0
	v_fmamk_f32 v0, v0, 0x2a800000, v204
	v_rsq_f32_e32 v138, v0
	v_ffbh_u32_e32 v0, v145
	v_min_u32_e32 v0, 32, v0
	v_lshlrev_b64 v[144:145], v0, v[144:145]
	v_min_u32_e32 v139, 1, v144
	v_or_b32_e32 v139, v145, v139
	v_cvt_f32_u32_e32 v139, v139
	v_sub_u32_e32 v0, 32, v0
	v_ldexp_f32 v0, v139, v0
	v_fmamk_f32 v0, v0, 0x2a800000, v204
	v_rsq_f32_e32 v143, v0
	v_ffbh_u32_e32 v0, v141
	v_min_u32_e32 v0, 32, v0
	v_lshlrev_b64 v[140:141], v0, v[140:141]
	v_min_u32_e32 v139, 1, v140
	v_or_b32_e32 v139, v141, v139
	v_cvt_f32_u32_e32 v139, v139
	v_sub_u32_e32 v0, 32, v0
	v_ldexp_f32 v0, v139, v0
	v_fmamk_f32 v0, v0, 0x2a800000, v204
	v_rsq_f32_e32 v139, v0
	v_ffbh_u32_e32 v0, v135
	v_min_u32_e32 v0, 32, v0
	v_lshlrev_b64 v[134:135], v0, v[134:135]
	v_min_u32_e32 v134, 1, v134
	v_or_b32_e32 v134, v135, v134
	v_cvt_f32_u32_e32 v134, v134
	v_sub_u32_e32 v0, 32, v0
	v_ldexp_f32 v0, v134, v0
	v_fmamk_f32 v0, v0, 0x2a800000, v204
	v_rsq_f32_e32 v134, v0
	v_ffbh_u32_e32 v0, v131
	v_min_u32_e32 v0, 32, v0
	v_lshlrev_b64 v[130:131], v0, v[130:131]
	v_min_u32_e32 v130, 1, v130
	v_or_b32_e32 v130, v131, v130
	v_cvt_f32_u32_e32 v130, v130
	v_sub_u32_e32 v0, 32, v0
	v_ldexp_f32 v0, v130, v0
	v_fmamk_f32 v0, v0, 0x2a800000, v204
	v_rsq_f32_e32 v130, v0
	v_ffbh_u32_e32 v0, v137
	v_min_u32_e32 v0, 32, v0
	v_lshlrev_b64 v[136:137], v0, v[136:137]
	v_min_u32_e32 v131, 1, v136
	v_or_b32_e32 v131, v137, v131
	v_cvt_f32_u32_e32 v131, v131
	v_sub_u32_e32 v0, 32, v0
	v_ldexp_f32 v0, v131, v0
	v_fmamk_f32 v0, v0, 0x2a800000, v204
	v_rsq_f32_e32 v135, v0
	v_ffbh_u32_e32 v0, v133
	v_min_u32_e32 v0, 32, v0
	v_lshlrev_b64 v[132:133], v0, v[132:133]
	v_min_u32_e32 v131, 1, v132
	v_or_b32_e32 v131, v133, v131
	v_cvt_f32_u32_e32 v131, v131
	v_sub_u32_e32 v0, 32, v0
	v_ldexp_f32 v0, v131, v0
	v_fmamk_f32 v0, v0, 0x2a800000, v204
	v_rsq_f32_e32 v131, v0
	v_lshl_add_u32 v0, s26, 8, v184
	v_cmp_lt_i32_e32 vcc, -1, v0
	s_and_saveexec_b64 s[24:25], vcc
	s_cbranch_execz .LBB0_330
; __device__ __forceinline__ unsigned cvt_pk_bf16(float lo, float hi) { unsigned r; asm volatile("v_cvt_pk_bf16_f32 %0, %1, %2" : "=v"(r) : "v"(lo), "v"(hi)); return r; }
;     __device__ __forceinline__ void operator()(const f32x4 (&acc)[2][2][4][2], const Unit& u, int wr, int wc, int fr, int fq) const {
;     ...
;             for (int m = 0; m < 4; ++m) { const int f = row0 + ai * HALF + m * 16; if (f < 0) continue; const int kvh = f >> 6, d = f & 63;
; #pragma unroll
;                 for (int bj = 0; bj < 2; ++bj) { const int col = col0 + bj * HALF; const float bs = bias[(size_t)(col >> 12) * ldb + f + row_off];
;                     const f32x4 v0 = acc[ai][bj][m][0] * r0[bj] + bs, v1 = acc[ai][bj][m][1] * r1[bj] + bs;
;                     u32x4 w; w.x = cvt_pk_bf16(v0[0], v0[1]); w.y = cvt_pk_bf16(v0[2], v0[3]); w.z = cvt_pk_bf16(v1[0], v1[1]); w.w = cvt_pk_bf16(v1[2], v1[3]);
;                     const int b = col >> 12, s = col & 4095, x = (s & 31) >> 3;
;                     *(u32x4*)(VF + ((size_t)((b * nkv + kvh) * 128 + (s >> 5)) << 12) + ((d >> 5) * 2 + (x >> 1)) * 1024 + ((x & 1) * 32 + (d & 31)) * 16) = w; } }
	s_mul_i32 s28, s19, 0x3000
	s_mul_hi_i32 s26, s19, 0x3000
	s_add_u32 s28, s54, s28
	s_addc_u32 s29, s58, s26
	v_lshl_add_u64 v[132:133], v[0:1], 2, s[28:29]
	s_lshl_b32 s68, s51, 2
	v_lshl_add_u64 v[132:133], v[132:133], 0, s[68:69]
	global_load_dword v136, v[132:133], off
	v_lshrrev_b32_e32 v137, 6, v0
	s_lshl_b32 s26, s19, s41
	s_waitcnt vmcnt(0)
	v_pk_fma_f32 v[126:127], v[126:127], v[172:173], v[136:137] op_sel_hi:[1,1,0]
	v_pk_fma_f32 v[140:141], v[124:125], v[178:179], v[136:137] op_sel_hi:[1,1,0]
	v_pk_fma_f32 v[124:125], v[122:123], v[174:175], v[136:137] op_sel_hi:[1,1,0]
	v_cvt_pk_bf16_f32 v122, v126, v127
	v_add_u32_e32 v126, s26, v137
	s_lshr_b32 s26, s17, 5
	v_lshl_or_b32 v126, v126, 7, s26
	v_pk_fma_f32 v[128:129], v[128:129], v[176:177], v[136:137] op_sel_hi:[1,1,0]
	v_ashrrev_i32_e32 v127, 31, v126
	v_cvt_pk_bf16_f32 v123, v128, v129
	v_lshlrev_b64 v[128:129], 12, v[126:127]
	v_lshl_add_u64 v[128:129], v[166:167], 0, v[128:129]
	v_cvt_pk_bf16_f32 v124, v124, v125
	v_cvt_pk_bf16_f32 v125, v140, v141
	global_store_dwordx4 v[128:129], v[122:125], off
	s_nop 1
	v_mov_b32_e32 v122, v136
	v_pk_fma_f32 v[118:119], v[118:119], v[142:143], v[122:123] op_sel_hi:[1,1,0]
	v_pk_fma_f32 v[124:125], v[116:117], v[130:131], v[122:123] op_sel_hi:[1,1,0]
	v_pk_fma_f32 v[116:117], v[114:115], v[138:139], v[122:123] op_sel_hi:[1,1,0]
	v_cvt_pk_bf16_f32 v114, v118, v119
	v_or_b32_e32 v118, 4, v126
	v_ashrrev_i32_e32 v119, 31, v118
	v_lshlrev_b64 v[118:119], 12, v[118:119]
	v_lshl_add_u64 v[118:119], v[166:167], 0, v[118:119]
	v_pk_fma_f32 v[120:121], v[120:121], v[134:135], v[122:123] op_sel_hi:[1,1,0]
	s_nop 0
	v_cvt_pk_bf16_f32 v115, v120, v121
	v_cvt_pk_bf16_f32 v116, v116, v117
	v_cvt_pk_bf16_f32 v117, v124, v125
	global_store_dwordx4 v[118:119], v[114:117], off
.LBB0_330:
	s_or_b64 exec, exec, s[24:25]
	s_movk_i32 s24, 0xffef
	v_cmp_lt_i32_e32 vcc, s24, v0
	s_and_saveexec_b64 s[24:25], vcc
	s_cbranch_execz .LBB0_332
	s_mul_i32 s28, s19, 0x3000
	s_mul_hi_i32 s26, s19, 0x3000
	s_add_u32 s28, s54, s28
	s_addc_u32 s29, s58, s26
	v_lshl_add_u64 v[116:117], v[0:1], 2, s[28:29]
	s_lshl_b32 s68, s51, 2
	v_lshl_add_u64 v[116:117], v[116:117], 0, s[68:69]
	global_load_dword v118, v[116:117], off offset:64
	v_lshrrev_b32_e32 v119, 6, v0
	s_lshl_b32 s26, s19, s41
	v_or_b32_e32 v114, 16, v0
	v_and_or_b32 v114, v114, 31, v183
	v_lshlrev_b32_e32 v114, 4, v114
	v_mov_b32_e32 v115, v1
	s_waitcnt vmcnt(0)
	v_pk_fma_f32 v[110:111], v[110:111], v[172:173], v[118:119] op_sel_hi:[1,1,0]
	v_pk_fma_f32 v[120:121], v[108:109], v[178:179], v[118:119] op_sel_hi:[1,1,0]
	v_pk_fma_f32 v[108:109], v[106:107], v[174:175], v[118:119] op_sel_hi:[1,1,0]
	v_cvt_pk_bf16_f32 v106, v110, v111
	v_add_u32_e32 v110, s26, v119
	s_lshr_b32 s26, s17, 5
	v_lshl_or_b32 v110, v110, 7, s26
	v_pk_fma_f32 v[112:113], v[112:113], v[176:177], v[118:119] op_sel_hi:[1,1,0]
	v_ashrrev_i32_e32 v111, 31, v110
	v_cvt_pk_bf16_f32 v107, v112, v113
	v_lshlrev_b64 v[112:113], 12, v[110:111]
	v_lshl_add_u64 v[112:113], v[164:165], 0, v[112:113]
	v_lshl_add_u64 v[112:113], v[112:113], 0, v[114:115]
	v_cvt_pk_bf16_f32 v108, v108, v109
	v_cvt_pk_bf16_f32 v109, v120, v121
	global_store_dwordx4 v[112:113], v[106:109], off
	s_nop 1
	v_mov_b32_e32 v106, v118
	v_pk_fma_f32 v[102:103], v[102:103], v[142:143], v[106:107] op_sel_hi:[1,1,0]
	v_pk_fma_f32 v[108:109], v[100:101], v[130:131], v[106:107] op_sel_hi:[1,1,0]
	v_pk_fma_f32 v[100:101], v[98:99], v[138:139], v[106:107] op_sel_hi:[1,1,0]
	v_cvt_pk_bf16_f32 v98, v102, v103
	v_or_b32_e32 v102, 4, v110
	v_ashrrev_i32_e32 v103, 31, v102
	v_lshlrev_b64 v[102:103], 12, v[102:103]
	v_lshl_add_u64 v[102:103], v[164:165], 0, v[102:103]
	v_lshl_add_u64 v[102:103], v[102:103], 0, v[114:115]
	v_pk_fma_f32 v[104:105], v[104:105], v[134:135], v[106:107] op_sel_hi:[1,1,0]
	s_nop 0
	v_cvt_pk_bf16_f32 v99, v104, v105
	v_cvt_pk_bf16_f32 v100, v100, v101
	v_cvt_pk_bf16_f32 v101, v108, v109
	global_store_dwordx4 v[102:103], v[98:101], off
.LBB0_332:
	s_or_b64 exec, exec, s[24:25]
	s_movk_i32 s24, 0xffdf
	v_cmp_lt_i32_e32 vcc, s24, v0
	s_and_saveexec_b64 s[24:25], vcc
	s_cbranch_execz .LBB0_334
	s_mul_i32 s28, s19, 0x3000
	s_mul_hi_i32 s26, s19, 0x3000
	s_add_u32 s28, s54, s28
	s_addc_u32 s29, s58, s26
	v_ashrrev_i32_e32 v99, 31, v0
	v_mov_b32_e32 v98, v0
	v_lshl_add_u64 v[98:99], v[98:99], 2, s[28:29]
	s_lshl_b32 s68, s51, 2
	v_lshl_add_u64 v[98:99], v[98:99], 0, s[68:69]
	global_load_dword v100, v[98:99], off offset:128
	v_lshrrev_b32_e32 v101, 6, v0
	s_lshl_b32 s26, s19, s41
	s_waitcnt vmcnt(0)
	v_pk_fma_f32 v[94:95], v[94:95], v[172:173], v[100:101] op_sel_hi:[1,1,0]
	v_pk_fma_f32 v[102:103], v[92:93], v[178:179], v[100:101] op_sel_hi:[1,1,0]
	v_pk_fma_f32 v[92:93], v[90:91], v[174:175], v[100:101] op_sel_hi:[1,1,0]
	v_cvt_pk_bf16_f32 v90, v94, v95
	v_add_u32_e32 v94, s26, v101
	s_lshr_b32 s26, s17, 5
	v_lshl_or_b32 v94, v94, 7, s26
	v_pk_fma_f32 v[96:97], v[96:97], v[176:177], v[100:101] op_sel_hi:[1,1,0]
	v_ashrrev_i32_e32 v95, 31, v94
	v_cvt_pk_bf16_f32 v91, v96, v97
	v_lshlrev_b64 v[96:97], 12, v[94:95]
	v_lshl_add_u64 v[96:97], v[166:167], 0, v[96:97]
	v_cvt_pk_bf16_f32 v92, v92, v93
	v_cvt_pk_bf16_f32 v93, v102, v103
	global_store_dwordx4 v[96:97], v[90:93], off offset:2048
	s_nop 1
	v_mov_b32_e32 v90, v100
	v_pk_fma_f32 v[86:87], v[86:87], v[142:143], v[90:91] op_sel_hi:[1,1,0]
	v_pk_fma_f32 v[92:93], v[84:85], v[130:131], v[90:91] op_sel_hi:[1,1,0]
	v_pk_fma_f32 v[84:85], v[82:83], v[138:139], v[90:91] op_sel_hi:[1,1,0]
	v_cvt_pk_bf16_f32 v82, v86, v87
	v_or_b32_e32 v86, 4, v94
	v_ashrrev_i32_e32 v87, 31, v86
	v_lshlrev_b64 v[86:87], 12, v[86:87]
	v_lshl_add_u64 v[86:87], v[166:167], 0, v[86:87]
	v_pk_fma_f32 v[88:89], v[88:89], v[134:135], v[90:91] op_sel_hi:[1,1,0]
	s_nop 0
	v_cvt_pk_bf16_f32 v83, v88, v89
	v_cvt_pk_bf16_f32 v84, v84, v85
	v_cvt_pk_bf16_f32 v85, v92, v93
	global_store_dwordx4 v[86:87], v[82:85], off offset:2048
; __device__ __forceinline__ unsigned cvt_pk_bf16(float lo, float hi) { unsigned r; asm volatile("v_cvt_pk_bf16_f32 %0, %1, %2" : "=v"(r) : "v"(lo), "v"(hi)); return r; }
;     __device__ __forceinline__ void operator()(const f32x4 (&acc)[2][2][4][2], const Unit& u, int wr, int wc, int fr, int fq) const {
;     ...
;             for (int m = 0; m < 4; ++m) { const int f = row0 + ai * HALF + m * 16; if (f < 0) continue; const int kvh = f >> 6, d = f & 63;
; #pragma unroll
;                 for (int bj = 0; bj < 2; ++bj) { const int col = col0 + bj * HALF; const float bs = bias[(size_t)(col >> 12) * ldb + f + row_off];
;                     const f32x4 v0 = acc[ai][bj][m][0] * r0[bj] + bs, v1 = acc[ai][bj][m][1] * r1[bj] + bs;
;                     u32x4 w; w.x = cvt_pk_bf16(v0[0], v0[1]); w.y = cvt_pk_bf16(v0[2], v0[3]); w.z = cvt_pk_bf16(v1[0], v1[1]); w.w = cvt_pk_bf16(v1[2], v1[3]);
;                     const int b = col >> 12, s = col & 4095, x = (s & 31) >> 3;
;                     *(u32x4*)(VF + ((size_t)((b * nkv + kvh) * 128 + (s >> 5)) << 12) + ((d >> 5) * 2 + (x >> 1)) * 1024 + ((x & 1) * 32 + (d & 31)) * 16) = w; } }
.LBB0_334:
	s_or_b64 exec, exec, s[24:25]
	s_movk_i32 s24, 0xffcf
	v_cmp_lt_i32_e32 vcc, s24, v0
	s_and_saveexec_b64 s[24:25], vcc
	s_cbranch_execz .LBB0_336
	s_mul_i32 s28, s19, 0x3000
	s_mul_hi_i32 s26, s19, 0x3000
	s_add_u32 s28, s54, s28
	s_addc_u32 s29, s58, s26
	v_lshl_add_u64 v[84:85], v[0:1], 2, s[28:29]
	s_lshl_b32 s68, s51, 2
	v_lshl_add_u64 v[84:85], v[84:85], 0, s[68:69]
	global_load_dword v86, v[84:85], off offset:192
	v_lshrrev_b32_e32 v87, 6, v0
	s_lshl_b32 s26, s19, s41
	v_or_b32_e32 v82, 16, v0
	v_and_or_b32 v82, v82, 31, v183
	v_lshlrev_b32_e32 v82, 4, v82
	v_mov_b32_e32 v83, v1
	s_waitcnt vmcnt(0)
	v_pk_fma_f32 v[78:79], v[78:79], v[172:173], v[86:87] op_sel_hi:[1,1,0]
	v_pk_fma_f32 v[88:89], v[76:77], v[178:179], v[86:87] op_sel_hi:[1,1,0]
	v_pk_fma_f32 v[76:77], v[74:75], v[174:175], v[86:87] op_sel_hi:[1,1,0]
	v_cvt_pk_bf16_f32 v74, v78, v79
	v_add_u32_e32 v78, s26, v87
	s_lshr_b32 s26, s17, 5
	v_lshl_or_b32 v78, v78, 7, s26
	v_pk_fma_f32 v[80:81], v[80:81], v[176:177], v[86:87] op_sel_hi:[1,1,0]
	v_ashrrev_i32_e32 v79, 31, v78
	v_cvt_pk_bf16_f32 v75, v80, v81
	v_lshlrev_b64 v[80:81], 12, v[78:79]
	v_lshl_add_u64 v[80:81], v[164:165], 0, v[80:81]
	v_lshl_add_u64 v[80:81], v[80:81], 0, v[82:83]
	v_cvt_pk_bf16_f32 v76, v76, v77
	v_cvt_pk_bf16_f32 v77, v88, v89
	global_store_dwordx4 v[80:81], v[74:77], off offset:2048
	s_nop 1
	v_mov_b32_e32 v74, v86
	v_pk_fma_f32 v[70:71], v[70:71], v[142:143], v[74:75] op_sel_hi:[1,1,0]
	v_pk_fma_f32 v[76:77], v[68:69], v[130:131], v[74:75] op_sel_hi:[1,1,0]
	v_pk_fma_f32 v[68:69], v[66:67], v[138:139], v[74:75] op_sel_hi:[1,1,0]
	v_cvt_pk_bf16_f32 v66, v70, v71
	v_or_b32_e32 v70, 4, v78
	v_ashrrev_i32_e32 v71, 31, v70
	v_lshlrev_b64 v[70:71], 12, v[70:71]
	v_lshl_add_u64 v[70:71], v[164:165], 0, v[70:71]
	v_lshl_add_u64 v[70:71], v[70:71], 0, v[82:83]
	v_pk_fma_f32 v[72:73], v[72:73], v[134:135], v[74:75] op_sel_hi:[1,1,0]
	s_nop 0
	v_cvt_pk_bf16_f32 v67, v72, v73
	v_cvt_pk_bf16_f32 v68, v68, v69
	v_cvt_pk_bf16_f32 v69, v76, v77
	global_store_dwordx4 v[70:71], v[66:69], off offset:2048
.LBB0_336:
	s_or_b64 exec, exec, s[24:25]
	s_movk_i32 s24, 0xff7f
	v_cmp_lt_i32_e32 vcc, s24, v0
	s_and_saveexec_b64 s[24:25], vcc
	s_cbranch_execz .LBB0_338
	s_mul_i32 s28, s19, 0x3000
	s_mul_hi_i32 s26, s19, 0x3000
	s_add_u32 s28, s54, s28
	v_add_u32_e32 v66, 0x80, v0
	v_mov_b32_e32 v67, v1
	s_addc_u32 s29, s58, s26
	v_lshrrev_b32_e32 v69, 6, v66
	v_lshl_add_u64 v[66:67], v[66:67], 2, s[28:29]
	s_lshl_b32 s68, s51, 2
	v_lshl_add_u64 v[66:67], v[66:67], 0, s[68:69]
	global_load_dword v68, v[66:67], off
	s_lshl_b32 s26, s19, s41
	s_waitcnt vmcnt(0)
	v_pk_fma_f32 v[62:63], v[62:63], v[172:173], v[68:69] op_sel_hi:[1,1,0]
	v_pk_fma_f32 v[70:71], v[60:61], v[178:179], v[68:69] op_sel_hi:[1,1,0]
	v_pk_fma_f32 v[60:61], v[58:59], v[174:175], v[68:69] op_sel_hi:[1,1,0]
	v_cvt_pk_bf16_f32 v58, v62, v63
	v_add_u32_e32 v62, s26, v69
	s_lshr_b32 s26, s17, 5
	v_lshl_or_b32 v62, v62, 7, s26
	v_pk_fma_f32 v[64:65], v[64:65], v[176:177], v[68:69] op_sel_hi:[1,1,0]
	v_ashrrev_i32_e32 v63, 31, v62
	v_cvt_pk_bf16_f32 v59, v64, v65
	v_lshlrev_b64 v[64:65], 12, v[62:63]
	v_lshl_add_u64 v[64:65], v[166:167], 0, v[64:65]
	v_cvt_pk_bf16_f32 v60, v60, v61
	v_cvt_pk_bf16_f32 v61, v70, v71
	global_store_dwordx4 v[64:65], v[58:61], off
	s_nop 1
	v_mov_b32_e32 v58, v68
	v_pk_fma_f32 v[54:55], v[54:55], v[142:143], v[58:59] op_sel_hi:[1,1,0]
	v_pk_fma_f32 v[60:61], v[52:53], v[130:131], v[58:59] op_sel_hi:[1,1,0]
	v_pk_fma_f32 v[52:53], v[50:51], v[138:139], v[58:59] op_sel_hi:[1,1,0]
	v_cvt_pk_bf16_f32 v50, v54, v55
	v_or_b32_e32 v54, 4, v62
	v_ashrrev_i32_e32 v55, 31, v54
	v_lshlrev_b64 v[54:55], 12, v[54:55]
	v_lshl_add_u64 v[54:55], v[166:167], 0, v[54:55]
	v_pk_fma_f32 v[56:57], v[56:57], v[134:135], v[58:59] op_sel_hi:[1,1,0]
	s_nop 0
	v_cvt_pk_bf16_f32 v51, v56, v57
	v_cvt_pk_bf16_f32 v52, v52, v53
	v_cvt_pk_bf16_f32 v53, v60, v61
	global_store_dwordx4 v[54:55], v[50:53], off
; __device__ __forceinline__ unsigned cvt_pk_bf16(float lo, float hi) { unsigned r; asm volatile("v_cvt_pk_bf16_f32 %0, %1, %2" : "=v"(r) : "v"(lo), "v"(hi)); return r; }
;     __device__ __forceinline__ void operator()(const f32x4 (&acc)[2][2][4][2], const Unit& u, int wr, int wc, int fr, int fq) const {
;     ...
;             for (int m = 0; m < 4; ++m) { const int f = row0 + ai * HALF + m * 16; if (f < 0) continue; const int kvh = f >> 6, d = f & 63;
; #pragma unroll
;                 for (int bj = 0; bj < 2; ++bj) { const int col = col0 + bj * HALF; const float bs = bias[(size_t)(col >> 12) * ldb + f + row_off];
;                     const f32x4 v0 = acc[ai][bj][m][0] * r0[bj] + bs, v1 = acc[ai][bj][m][1] * r1[bj] + bs;
;                     u32x4 w; w.x = cvt_pk_bf16(v0[0], v0[1]); w.y = cvt_pk_bf16(v0[2], v0[3]); w.z = cvt_pk_bf16(v1[0], v1[1]); w.w = cvt_pk_bf16(v1[2], v1[3]);
;                     const int b = col >> 12, s = col & 4095, x = (s & 31) >> 3;
;                     *(u32x4*)(VF + ((size_t)((b * nkv + kvh) * 128 + (s >> 5)) << 12) + ((d >> 5) * 2 + (x >> 1)) * 1024 + ((x & 1) * 32 + (d & 31)) * 16) = w; } }
.LBB0_338:
	s_or_b64 exec, exec, s[24:25]
	s_movk_i32 s24, 0xff6f
	v_cmp_lt_i32_e32 vcc, s24, v0
	s_and_saveexec_b64 s[24:25], vcc
	s_cbranch_execz .LBB0_340
	v_add_u32_e32 v54, 0x90, v0
	s_mul_i32 s28, s19, 0x3000
	v_lshrrev_b32_e32 v50, 4, v54
	s_mul_hi_i32 s26, s19, 0x3000
	s_add_u32 s28, s54, s28
	v_mov_b32_e32 v55, v1
	v_and_or_b32 v50, v50, 2, v182
	s_addc_u32 s29, s58, s26
	v_lshrrev_b32_e32 v57, 6, v54
	v_lshlrev_b32_e32 v52, 10, v50
	v_and_or_b32 v50, v54, 31, v183
	v_lshl_add_u64 v[54:55], v[54:55], 2, s[28:29]
	s_lshl_b32 s68, s51, 2
	v_lshl_add_u64 v[54:55], v[54:55], 0, s[68:69]
	global_load_dword v56, v[54:55], off
	s_lshl_b32 s26, s19, s41
	v_mov_b32_e32 v53, v1
	v_lshlrev_b32_e32 v50, 4, v50
	v_mov_b32_e32 v51, v1
	s_waitcnt vmcnt(0)
	v_pk_fma_f32 v[46:47], v[46:47], v[172:173], v[56:57] op_sel_hi:[1,1,0]
	v_pk_fma_f32 v[58:59], v[44:45], v[178:179], v[56:57] op_sel_hi:[1,1,0]
	v_pk_fma_f32 v[44:45], v[42:43], v[174:175], v[56:57] op_sel_hi:[1,1,0]
	v_cvt_pk_bf16_f32 v42, v46, v47
	v_add_u32_e32 v46, s26, v57
	s_lshr_b32 s26, s17, 5
	v_lshl_or_b32 v46, v46, 7, s26
	v_pk_fma_f32 v[48:49], v[48:49], v[176:177], v[56:57] op_sel_hi:[1,1,0]
	v_ashrrev_i32_e32 v47, 31, v46
	v_cvt_pk_bf16_f32 v43, v48, v49
	v_lshlrev_b64 v[48:49], 12, v[46:47]
	v_lshl_add_u64 v[48:49], s[12:13], 0, v[48:49]
	v_lshl_add_u64 v[48:49], v[48:49], 0, v[52:53]
	v_lshl_add_u64 v[48:49], v[48:49], 0, v[50:51]
	v_cvt_pk_bf16_f32 v44, v44, v45
	v_cvt_pk_bf16_f32 v45, v58, v59
	global_store_dwordx4 v[48:49], v[42:45], off
	s_nop 1
	v_mov_b32_e32 v42, v56
	v_pk_fma_f32 v[38:39], v[38:39], v[142:143], v[42:43] op_sel_hi:[1,1,0]
	v_pk_fma_f32 v[44:45], v[36:37], v[130:131], v[42:43] op_sel_hi:[1,1,0]
	v_pk_fma_f32 v[36:37], v[34:35], v[138:139], v[42:43] op_sel_hi:[1,1,0]
	v_cvt_pk_bf16_f32 v34, v38, v39
	v_or_b32_e32 v38, 4, v46
	v_ashrrev_i32_e32 v39, 31, v38
	v_lshlrev_b64 v[38:39], 12, v[38:39]
	v_lshl_add_u64 v[38:39], s[12:13], 0, v[38:39]
	v_lshl_add_u64 v[38:39], v[38:39], 0, v[52:53]
	v_lshl_add_u64 v[38:39], v[38:39], 0, v[50:51]
	v_pk_fma_f32 v[40:41], v[40:41], v[134:135], v[42:43] op_sel_hi:[1,1,0]
	s_nop 0
	v_cvt_pk_bf16_f32 v35, v40, v41
	v_cvt_pk_bf16_f32 v36, v36, v37
	v_cvt_pk_bf16_f32 v37, v44, v45
	global_store_dwordx4 v[38:39], v[34:37], off
.LBB0_340:
	s_or_b64 exec, exec, s[24:25]
	s_movk_i32 s24, 0xff5f
	v_cmp_lt_i32_e32 vcc, s24, v0
	s_and_saveexec_b64 s[24:25], vcc
	s_cbranch_execz .LBB0_342
	s_mul_i32 s28, s19, 0x3000
	s_mul_hi_i32 s26, s19, 0x3000
	s_add_u32 s28, s54, s28
	v_add_u32_e32 v34, 0xa0, v0
	v_mov_b32_e32 v35, v1
	s_addc_u32 s29, s58, s26
	v_lshrrev_b32_e32 v39, 6, v34
	v_lshrrev_b32_e32 v36, 4, v34
	v_lshl_add_u64 v[34:35], v[34:35], 2, s[28:29]
	s_lshl_b32 s68, s51, 2
	v_lshl_add_u64 v[34:35], v[34:35], 0, s[68:69]
	global_load_dword v38, v[34:35], off
	s_lshl_b32 s26, s19, s41
	v_and_or_b32 v36, v36, 2, v182
	v_lshlrev_b32_e32 v36, 10, v36
	v_mov_b32_e32 v37, v1
	s_waitcnt vmcnt(0)
	v_pk_fma_f32 v[30:31], v[30:31], v[172:173], v[38:39] op_sel_hi:[1,1,0]
	v_pk_fma_f32 v[40:41], v[28:29], v[178:179], v[38:39] op_sel_hi:[1,1,0]
	v_pk_fma_f32 v[28:29], v[26:27], v[174:175], v[38:39] op_sel_hi:[1,1,0]
	v_cvt_pk_bf16_f32 v26, v30, v31
	v_add_u32_e32 v30, s26, v39
	s_lshr_b32 s26, s17, 5
	v_lshl_or_b32 v30, v30, 7, s26
	v_pk_fma_f32 v[32:33], v[32:33], v[176:177], v[38:39] op_sel_hi:[1,1,0]
	v_ashrrev_i32_e32 v31, 31, v30
	v_cvt_pk_bf16_f32 v27, v32, v33
	v_lshlrev_b64 v[32:33], 12, v[30:31]
	v_lshl_add_u64 v[32:33], s[12:13], 0, v[32:33]
	v_lshl_add_u64 v[32:33], v[32:33], 0, v[36:37]
	v_lshl_add_u64 v[32:33], v[32:33], 0, v[162:163]
	v_cvt_pk_bf16_f32 v28, v28, v29
	v_cvt_pk_bf16_f32 v29, v40, v41
	global_store_dwordx4 v[32:33], v[26:29], off
	s_nop 1
	v_mov_b32_e32 v26, v38
	v_pk_fma_f32 v[22:23], v[22:23], v[142:143], v[26:27] op_sel_hi:[1,1,0]
	v_pk_fma_f32 v[28:29], v[20:21], v[130:131], v[26:27] op_sel_hi:[1,1,0]
	v_pk_fma_f32 v[20:21], v[18:19], v[138:139], v[26:27] op_sel_hi:[1,1,0]
	v_cvt_pk_bf16_f32 v18, v22, v23
	v_or_b32_e32 v22, 4, v30
	v_ashrrev_i32_e32 v23, 31, v22
	v_lshlrev_b64 v[22:23], 12, v[22:23]
	v_lshl_add_u64 v[22:23], s[12:13], 0, v[22:23]
	v_lshl_add_u64 v[22:23], v[22:23], 0, v[36:37]
	v_lshl_add_u64 v[22:23], v[22:23], 0, v[162:163]
	v_pk_fma_f32 v[24:25], v[24:25], v[134:135], v[26:27] op_sel_hi:[1,1,0]
	s_nop 0
	v_cvt_pk_bf16_f32 v19, v24, v25
	v_cvt_pk_bf16_f32 v20, v20, v21
	v_cvt_pk_bf16_f32 v21, v28, v29
	global_store_dwordx4 v[22:23], v[18:21], off
